# v037
# speedup vs baseline: 1.0006x; 1.0006x over previous
; __device__ __forceinline__ void partialSM(f32x16& p0, f32x16& p1, float& m_reg, float& mn, float& alpha) {
;     ...
;   else { mn = fmaxf(m_reg, pmax); alpha = __builtin_amdgcn_exp2f((m_reg - mn) * C); m_reg = mn; }
;   float mnC = -mn * C;
;   for (int r = 0; r < 16; ++r) p0[r] = fmaf(p0[r], C, mnC); for (int r = 0; r < 16; ++r) p1[r] = fmaf(p1[r], C, mnC);
;   for (int r = 0; r < 16; ++r) p0[r] = __builtin_amdgcn_exp2f(p0[r]);
; }
; __device__ __forceinline__ void finishSM(f32x16& p0, f32x16& p1, float alpha, float& l_reg, bf16x8& pa0, bf16x8& pa1, bf16x8& pa2, bf16x8& pa3) {
;   for (int r = 0; r < 16; ++r) p1[r] = __builtin_amdgcn_exp2f(p1[r]);
;   float ps = 0; for (int r = 0; r < 16; ++r) ps += p0[r]; for (int r = 0; r < 16; ++r) ps += p1[r];
;   { auto rr = __builtin_amdgcn_permlane32_swap(__float_as_uint(ps), __float_as_uint(ps), false, false);
;     ps = __uint_as_float(rr[0]) + __uint_as_float(rr[1]); }
;   l_reg = l_reg * alpha + ps;
.LBB0_342:
	v_cndmask_b32_e64 v191, v144, v191, s[8:9]
	v_mul_f32_e32 v144, 0xbdd53b94, v191
	v_add_f32_e32 v145, v209, v210
	v_mov_b32_e32 v162, v144
	v_fmac_f32_e32 v145, v208, v189
	v_add_f32_e32 v189, v177, v178
	v_fmamk_f32 v80, v80, 0x3dd53b94, v144
	v_fmamk_f32 v81, v81, 0x3dd53b94, v144
	v_fmamk_f32 v82, v82, 0x3dd53b94, v144
	v_fmamk_f32 v83, v83, 0x3dd53b94, v144
	v_fmamk_f32 v84, v84, 0x3dd53b94, v144
	v_fmamk_f32 v85, v85, 0x3dd53b94, v144
	v_fmamk_f32 v86, v86, 0x3dd53b94, v144
	v_fmamk_f32 v87, v87, 0x3dd53b94, v144
	v_fmamk_f32 v88, v88, 0x3dd53b94, v144
	v_fmamk_f32 v89, v89, 0x3dd53b94, v144
	v_fmamk_f32 v90, v90, 0x3dd53b94, v144
	v_fmamk_f32 v91, v91, 0x3dd53b94, v144
	v_fmamk_f32 v92, v92, 0x3dd53b94, v144
	v_fmamk_f32 v93, v93, 0x3dd53b94, v144
	v_fmamk_f32 v94, v94, 0x3dd53b94, v144
	v_fmac_f32_e32 v162, 0x3dd53b94, v95
	v_fmac_f32_e32 v189, v145, v211
	v_exp_f32_e32 v218, v80
	v_exp_f32_e32 v220, v81
	v_exp_f32_e32 v221, v82
	v_exp_f32_e32 v222, v83
	v_exp_f32_e32 v223, v84
	v_exp_f32_e32 v225, v85
	v_exp_f32_e32 v224, v86
	v_exp_f32_e32 v226, v87
	v_exp_f32_e32 v211, v88
	v_exp_f32_e32 v212, v89
	v_exp_f32_e32 v213, v90
	v_exp_f32_e32 v215, v91
	v_exp_f32_e32 v214, v92
	v_exp_f32_e32 v216, v93
	v_exp_f32_e32 v217, v94
	v_exp_f32_e32 v219, v162
	s_add_i32 s13, s13, 1
	s_and_b64 s[4:5], s[4:5], exec
	v_fma_f32 v159, v65, s68, v144
	v_fma_f32 v158, v64, s68, v144
	v_fma_f32 v157, v67, s68, v144
	v_fma_f32 v156, v66, s68, v144
	v_fma_f32 v155, v69, s68, v144
	v_fma_f32 v154, v68, s68, v144
	v_fma_f32 v153, v71, s68, v144
	v_fma_f32 v152, v70, s68, v144
	v_fma_f32 v151, v73, s68, v144
	v_fma_f32 v150, v72, s68, v144
	v_fma_f32 v149, v75, s68, v144
	v_fma_f32 v148, v74, s68, v144
	v_fma_f32 v147, v77, s68, v144
	v_fma_f32 v146, v76, s68, v144
	v_fma_f32 v145, v79, s68, v144
	v_fma_f32 v144, v78, s68, v144
	s_cselect_b32 s31, 0, s13
	s_add_i32 s30, s30, 2
	s_and_b64 vcc, exec, s[10:11]
	s_cbranch_vccnz .LBB0_372
	v_mov_b32_e32 v208, v176
	s_branch .LBB0_331
